# norm row loop (NORM / NORM_MLP): nt cache-policy hint on the once-read f32 x-row loads; identical code size and placement
# speedup vs baseline: 1.0032x; 1.0032x over previous
.LBB0_74:
	global_load_dwordx4 v[12:15], v[4:5], off offset:-2048 nt
	global_load_dwordx4 v[16:19], v[4:5], off offset:-1024 nt
	global_load_dwordx4 v[20:23], v[4:5], off nt
	global_load_dwordx4 v[24:27], v[4:5], off offset:1024 nt
	s_cmpk_lt_u32 s6, 0x2800
	s_cselect_b32 s0, s76, 0x3000
	s_cmpk_gt_i32 s6, 0x1fff
	s_cselect_b32 s0, s0, 0
	s_lshl_b32 s0, s0, 2
	s_add_u32 s0, s4, s0
	s_addc_u32 s1, s5, 0
	v_lshl_add_u64 v[84:85], s[0:1], 0, v[0:1]
	global_load_dwordx4 v[52:55], v0, s[0:1]
	v_lshl_add_u64 v[84:85], v[84:85], 0, s[12:13]
	s_add_i32 s6, s6, s70
	global_load_dwordx4 v[56:59], v[84:85], off
	global_load_dwordx4 v[60:63], v0, s[0:1] offset:1024
	global_load_dwordx4 v[64:67], v[84:85], off offset:1024
	global_load_dwordx4 v[68:71], v0, s[0:1] offset:2048
	global_load_dwordx4 v[72:75], v[84:85], off offset:2048
	global_load_dwordx4 v[76:79], v0, s[0:1] offset:3072
	global_load_dwordx4 v[80:83], v[84:85], off offset:3072
	s_cmpk_gt_i32 s6, 0x2fff
	s_waitcnt vmcnt(11)
	v_pk_mul_f32 v[40:41], v[14:15], v[14:15]
	v_pk_mul_f32 v[42:43], v[12:13], v[12:13]
	s_nop 0
	v_pk_mov_b32 v[44:45], v[42:43], v[40:41] op_sel:[1,0]
	v_mov_b32_e32 v43, v41
	v_pk_add_f32 v[28:29], v[44:45], v[42:43]
	s_nop 0
	v_pk_add_f32 v[28:29], v[28:29], v[28:29] op_sel:[0,1] op_sel_hi:[1,0]
	s_waitcnt vmcnt(10)
	v_pk_mul_f32 v[46:47], v[18:19], v[18:19]
	v_pk_mul_f32 v[48:49], v[16:17], v[16:17]
	s_nop 0
	v_pk_mov_b32 v[50:51], v[48:49], v[46:47] op_sel:[1,0]
	v_mov_b32_e32 v49, v47
	v_pk_add_f32 v[30:31], v[50:51], v[48:49]
	s_nop 0
	v_pk_add_f32 v[30:31], v[30:31], v[30:31] op_sel:[0,1] op_sel_hi:[1,0]
	v_lshl_add_u64 v[4:5], v[4:5], 0, s[96:97]
	s_waitcnt vmcnt(8)
	v_mul_f32_e32 v32, v24, v24
	v_mul_f32_e32 v33, v25, v25
	v_mov_b32_e32 v29, v32
	v_mov_b32_e32 v31, v33
	v_pk_add_f32 v[28:29], v[28:29], v[30:31]
	v_mul_f32_e32 v30, v21, v21
	v_mul_f32_e32 v32, v23, v23
	v_mul_f32_e32 v34, v26, v26
	v_mul_f32_e32 v35, v27, v27
	v_pk_fma_f32 v[30:31], v[20:21], v[20:21], v[30:31] op_sel_hi:[1,1,0]
	v_pk_fma_f32 v[32:33], v[22:23], v[22:23], v[32:33] op_sel_hi:[1,1,0]
	v_mov_b32_e32 v31, v34
	v_mov_b32_e32 v33, v35
	v_pk_add_f32 v[30:31], v[30:31], v[32:33]
	s_nop 0
	v_pk_add_f32 v[28:29], v[28:29], v[30:31]
	s_nop 0
	v_add_f32_e32 v28, v28, v29
	ds_bpermute_b32 v29, v6, v28
	s_waitcnt lgkmcnt(0)
	v_add_f32_e32 v28, v28, v29
	ds_bpermute_b32 v29, v7, v28
	s_waitcnt lgkmcnt(0)
	v_add_f32_e32 v28, v28, v29
	ds_bpermute_b32 v29, v8, v28
	s_waitcnt lgkmcnt(0)
	v_add_f32_e32 v28, v28, v29
	ds_bpermute_b32 v29, v9, v28
	s_waitcnt lgkmcnt(0)
	v_add_f32_e32 v28, v28, v29
	ds_bpermute_b32 v29, v10, v28
	s_waitcnt lgkmcnt(0)
	v_add_f32_e32 v28, v28, v29
	ds_bpermute_b32 v29, v11, v28
	s_waitcnt lgkmcnt(0)
	v_add_f32_e32 v28, v28, v29
	v_fmamk_f32 v28, v28, 0x3a800000, v213
	v_cmp_gt_f32_e32 vcc, s7, v28
	v_mul_f32_e32 v29, 0x4b800000, v28
	s_nop 0
	v_cndmask_b32_e32 v28, v28, v29, vcc
	v_rsq_f32_e32 v28, v28
	s_nop 0
	v_mul_f32_e32 v29, 0x45800000, v28
	v_cndmask_b32_e32 v36, v28, v29, vcc
	v_pk_mul_f32 v[12:13], v[12:13], v[36:37] op_sel_hi:[1,0]
	v_pk_mul_f32 v[14:15], v[14:15], v[36:37] op_sel_hi:[1,0]
	v_pk_mul_f32 v[16:17], v[16:17], v[36:37] op_sel_hi:[1,0]
	v_pk_mul_f32 v[18:19], v[18:19], v[36:37] op_sel_hi:[1,0]
	v_pk_mul_f32 v[20:21], v[20:21], v[36:37] op_sel_hi:[1,0]
	v_pk_mul_f32 v[22:23], v[22:23], v[36:37] op_sel_hi:[1,0]
	v_pk_mul_f32 v[24:25], v[24:25], v[36:37] op_sel_hi:[1,0]
	v_pk_mul_f32 v[26:27], v[26:27], v[36:37] op_sel_hi:[1,0]
	s_waitcnt vmcnt(6)
	v_pk_add_f32 v[58:59], v[58:59], 1.0 op_sel_hi:[1,0]
	v_pk_add_f32 v[56:57], v[56:57], 1.0 op_sel_hi:[1,0]
	v_pk_fma_f32 v[34:35], v[58:59], v[14:15], v[54:55]
	v_pk_fma_f32 v[32:33], v[56:57], v[12:13], v[52:53]
	s_waitcnt vmcnt(4)
	v_pk_add_f32 v[66:67], v[66:67], 1.0 op_sel_hi:[1,0]
	v_pk_add_f32 v[64:65], v[64:65], 1.0 op_sel_hi:[1,0]
	v_pk_fma_f32 v[30:31], v[66:67], v[18:19], v[62:63]
	v_pk_fma_f32 v[28:29], v[64:65], v[16:17], v[60:61]
	s_waitcnt vmcnt(2)
	v_pk_add_f32 v[74:75], v[74:75], 1.0 op_sel_hi:[1,0]
	v_pk_add_f32 v[72:73], v[72:73], 1.0 op_sel_hi:[1,0]
	v_pk_fma_f32 v[22:23], v[74:75], v[22:23], v[70:71]
	v_pk_fma_f32 v[20:21], v[72:73], v[20:21], v[68:69]
	s_waitcnt vmcnt(0)
	v_pk_add_f32 v[80:81], v[80:81], 1.0 op_sel_hi:[1,0]
	v_pk_add_f32 v[82:83], v[82:83], 1.0 op_sel_hi:[1,0]
	v_pk_fma_f32 v[12:13], v[80:81], v[24:25], v[76:77]
	v_cvt_pk_bf16_f32 v16, v32, v33
	v_cvt_pk_bf16_f32 v17, v34, v35
	v_pk_fma_f32 v[14:15], v[82:83], v[26:27], v[78:79]
	global_store_dwordx2 v[2:3], v[16:17], off offset:-1536
	v_cvt_pk_bf16_f32 v18, v28, v29
	v_cvt_pk_bf16_f32 v19, v30, v31
	global_store_dwordx2 v[2:3], v[18:19], off offset:-1024
	v_cvt_pk_bf16_f32 v40, v20, v21
	v_cvt_pk_bf16_f32 v41, v22, v23
	v_cvt_pk_bf16_f32 v12, v12, v13
	v_cvt_pk_bf16_f32 v13, v14, v15
	global_store_dwordx2 v[2:3], v[40:41], off offset:-512
	global_store_dwordx2 v[2:3], v[12:13], off
	v_lshl_add_u64 v[2:3], v[2:3], 0, s[8:9]
	s_cbranch_scc0 .LBB0_74
